# v125 plus cross-unit K prefetch and half the scan renormalisation sweeps
# baseline (speedup 1.0000x reference)
; __device__ __forceinline__ void nat_phase(const Params& p, float* ldsf, int wave0, int nwaves) {
;     const int lane = threadIdx.x & 63, wid = __builtin_amdgcn_readfirstlane(threadIdx.x >> 6), l15 = lane & 15, lq = lane >> 4;
;     const u16* Qn = (const u16*)p.out; const u16* Kn = Qn + (size_t)NTOK * RW; const u16* VT = Kn + (size_t)NTOK * RW; const u16* Gn = VT + (size_t)NTOK * RW;
;     u16* MIX = (u16*)(p.ws + O_HN);
;     for (int item = wave0; item < 8192; item += nwaves) {
;         const int r = item & 255, h = (item >> 8) & 15, b = item >> 12;
;         const int rs = min(max(r - 4, 0), 248);
;         const u16* Qb = Qn + (size_t)(b * SEQ + r * 64) * RW + h * 64;
;         const u16* Kb = Kn + (size_t)(b * SEQ + rs * 64) * RW + h * 64;
;         const u16* Vb = VT + (size_t)((b * 16 + h) * 64) * SEQ + rs * 64;
;         float* tb = ldsf + wid * 256;
;         { const float* rpb = p.rpb + h * 465 + (rs - r + 7) * 31;
; #pragma unroll
;           for (int q = 0; q < 4; ++q) { const int e = lane + q * 64; if (e < 248) tb[e] = rpb[e]; } }
; #pragma unroll 1
;         for (int qt = 0; qt < 4; ++qt) {
;             const int c0 = qt * 16, cs0 = (qt == 0) ? 0 : (qt == 1 ? 8 : (qt == 2 ? 24 : 32));
;             const int c = c0 + l15, csq = min(max(c - 8, 0), 48);
;             const bf16x8 bq0 = *(const bf16x8*)(Qb + (size_t)c * RW + lq * 8), bq1 = *(const bf16x8*)(Qb + (size_t)c * RW + 32 + lq * 8);
.LBB0_413:
	s_cmp_lt_i32 s58, 5
	s_cselect_b64 s[0:1], -1, 0
	s_cmp_gt_i32 s59, 4
	s_cselect_b64 s[4:5], -1, 0
	s_and_b64 s[0:1], s[0:1], s[4:5]
	s_andn2_b64 vcc, exec, s[0:1]
	s_cbranch_vccnz .LBB0_628
	v_readfirstlane_b32 s0, v254
	v_and_b32_e32 v96, 63, v254
	s_cmp_lt_u32 s0, 0
	v_and_b32_e32 v65, 15, v254
	s_cbranch_scc1 .LBB0_555
	s_setprio 0
	s_lshr_b32 s1, s0, 6
	s_mov_b32 s64, s56
	s_and_b32 s65, s57, 0xffff
	s_brev_b32 s66, -2
	s_mov_b32 s67, 0x27000
	s_mov_b32 s68, s54
	s_and_b32 s69, s55, 0xffff
	s_mov_b32 s70, s66
	s_mov_b32 s71, s67
	s_mov_b32 s72, s50
	s_and_b32 s73, s51, 0xffff
	s_movk_i32 s74, 0x7440
	s_mov_b32 s75, s67
	v_and_b32_e32 v237, 15, v254
	v_bfe_u32 v238, v254, 4, 2
	v_and_b32_e32 v242, 63, v254
	v_lshlrev_b32_e32 v243, 4, v238
	v_lshl_add_u32 v224, v237, 11, v243
	v_lshl_add_u32 v226, v237, 15, v243
	v_lshrrev_b32_e32 v244, 2, v237
	v_and_b32_e32 v245, 3, v237
	v_lshl_add_u32 v244, v244, 3, v245
	v_lshl_add_u32 v225, v244, 11, v243
	v_lshlrev_b32_e32 v243, 3, v238
	v_lshl_add_u32 v227, v237, 11, v243
	v_lshl_add_u32 v228, v237, 12, v243
	v_xor_b32_e32 v248, 16, v242
	v_lshlrev_b32_e32 v248, 2, v248
	v_xor_b32_e32 v249, 32, v242
	v_lshlrev_b32_e32 v249, 2, v249
	s_cmp_lt_u32 s1, 4
	s_cselect_b64 vcc, -1, 0
	s_nop 3
	v_cndmask_b32_e32 v50, v226, v225, vcc
	s_and_b32 s4, s1, 3
	s_lshl_b32 s4, s4, 8
	s_add_u32 s4, s4, 0x1e800
	v_lshl_add_u32 v244, v242, 2, s4
	v_mov_b32_e32 v243, 0xf2c9f2ca
	ds_write_b32 v244, v243
	v_mov_b32_e32 v252, 0x3e38aa3b
	v_mov_b32_e32 v253, 0x3e38aa3b
	s_mov_b32 s95, 0
	s_mov_b32 s88, s2
	s_mov_b32 s94, s96
	s_cmpk_lg_u32 s96, 0x100
	s_cbranch_scc1 .Lmy_nat_unit
	s_and_b32 s88, s2, 7
	s_lshl_b32 s88, s88, 5
	s_lshr_b32 s4, s2, 3
	s_add_u32 s88, s88, s4
	s_movk_i32 s94, 0x100
	s_bfe_u32 s4, s2, 0x20003

; __device__ __forceinline__ void nat_phase(const Params& p, float* ldsf, int wave0, int nwaves) {
;     ...
;         const u16* Kb = Kn + (size_t)(b * SEQ + rs * 64) * RW + h * 64;
;     ...
;                 for (int hf = 0; hf < 2; ++hf) { const u16* kp = Kb + (size_t)(i * 64 + cs0 + (l15 >> 2) * 8 + hf * 4 + (l15 & 3)) * RW + lq * 8;
;                     const bf16x8 a0 = *(const bf16x8*)kp, a1 = *(const bf16x8*)(kp + 32); f32x4 z = {0.f, 0.f, 0.f, 0.f};
.Lmy_nat_p1k0:
	s_lshl_b32 s91, s83, 11
	s_add_u32 s91, s91, s77
	s_lshr_b32 s85, s1, 1
	s_lshl_b32 s85, s85, 13
	s_add_u32 s91, s91, s85
	s_and_b32 s85, s1, 1
	s_lshl_b32 s85, s85, 6
	s_add_u32 s91, s91, s85
	s_mov_b32 s93, 0x20000
	s_lshl_b32 s86, s1, 10
	s_mov_b32 m0, s86
	s_nop 0
	buffer_load_dwordx4 v50, s[68:71], s91 offen lds
	s_add_u32 m0, m0, 0x1000
	s_add_u32 s91, s91, s93
	buffer_load_dwordx4 v50, s[68:71], s91 offen lds
	s_add_u32 m0, m0, 0x1000
	s_add_u32 s91, s91, s93
	buffer_load_dwordx4 v50, s[68:71], s91 offen lds
	s_add_u32 m0, m0, 0x1000
	s_add_u32 s91, s91, s93
	buffer_load_dwordx4 v50, s[68:71], s91 offen lds
	s_add_u32 m0, m0, 0x1000
	s_add_u32 s91, s91, s93
	buffer_load_dwordx4 v50, s[68:71], s91 offen lds
	s_add_u32 m0, m0, 0x1000
	s_add_u32 s91, s91, s93
	buffer_load_dwordx4 v50, s[68:71], s91 offen lds
	s_add_u32 m0, m0, 0x1000
	s_add_u32 s91, s91, s93
	buffer_load_dwordx4 v50, s[68:71], s91 offen lds
	s_add_u32 m0, m0, 0x1000
	s_add_u32 s91, s91, s93
	buffer_load_dwordx4 v50, s[68:71], s91 offen lds
	s_add_u32 m0, m0, 0x1000
	s_add_u32 s91, s91, s93
	buffer_load_dwordx4 v50, s[68:71], s91 offen lds
	s_add_u32 m0, m0, 0x1000
	s_add_u32 s91, s91, s93
	buffer_load_dwordx4 v50, s[68:71], s91 offen lds
	s_add_u32 m0, m0, 0x1000
	s_add_u32 s91, s91, s93
	buffer_load_dwordx4 v50, s[68:71], s91 offen lds
	s_add_u32 m0, m0, 0x1000
	s_add_u32 s91, s91, s93
	buffer_load_dwordx4 v50, s[68:71], s91 offen lds
	s_add_u32 m0, m0, 0x1000
	s_add_u32 s91, s91, s93
	buffer_load_dwordx4 v50, s[68:71], s91 offen lds
	s_add_u32 m0, m0, 0x1000
	s_add_u32 s91, s91, s93
	buffer_load_dwordx4 v50, s[68:71], s91 offen lds
	s_add_u32 m0, m0, 0x1000
	s_add_u32 s91, s91, s93
	buffer_load_dwordx4 v50, s[68:71], s91 offen lds
	s_waitcnt vmcnt(0)
	s_branch .Lmy_nat_p1j

; __device__ __forceinline__ void nat_phase(const Params& p, float* ldsf, int wave0, int nwaves) {
;     ...
;     for (int item = wave0; item < 8192; item += nwaves) {
;         const int r = item & 255, h = (item >> 8) & 15, b = item >> 12;
;         const int rs = min(max(r - 4, 0), 248);
;         const u16* Qb = Qn + (size_t)(b * SEQ + r * 64) * RW + h * 64;
;         const u16* Kb = Kn + (size_t)(b * SEQ + rs * 64) * RW + h * 64;
;         const u16* Vb = VT + (size_t)((b * 16 + h) * 64) * SEQ + rs * 64;
;     ...
;                 for (int hf = 0; hf < 2; ++hf) { const u16* kp = Kb + (size_t)(i * 64 + cs0 + (l15 >> 2) * 8 + hf * 4 + (l15 & 3)) * RW + lq * 8;
;                     const bf16x8 a0 = *(const bf16x8*)kp, a1 = *(const bf16x8*)(kp + 32); f32x4 z = {0.f, 0.f, 0.f, 0.f};
.Lmy_nat_p3j:
	s_barrier
	s_mov_b32 s0, 0
	s_cmp_lt_u32 s1, 4
	s_cbranch_scc0 .Lmy_nat_p4j
	s_cmp_lt_u32 s16, 3
	s_cbranch_scc0 .Lmy_nat_p4x
	s_add_i32 s87, s82, 8
	s_min_i32 s87, s87, 32
	s_lshl_b32 s91, s87, 11
	s_add_u32 s91, s91, s77
	s_lshr_b32 s85, s1, 1
	s_lshl_b32 s85, s85, 13
	s_add_u32 s91, s91, s85
	s_and_b32 s85, s1, 1
	s_lshl_b32 s85, s85, 6
	s_add_u32 s91, s91, s85
	s_mov_b32 s93, 0x20000
	s_lshl_b32 s86, s1, 10
	s_mov_b32 m0, s86
	s_nop 0
	buffer_load_dwordx4 v50, s[68:71], s91 offen lds
	s_add_u32 m0, m0, 0x1000
	s_add_u32 s91, s91, s93
	buffer_load_dwordx4 v50, s[68:71], s91 offen lds
	s_add_u32 m0, m0, 0x1000
	s_add_u32 s91, s91, s93
	buffer_load_dwordx4 v50, s[68:71], s91 offen lds
	s_add_u32 m0, m0, 0x1000
	s_add_u32 s91, s91, s93
	buffer_load_dwordx4 v50, s[68:71], s91 offen lds
	s_add_u32 m0, m0, 0x1000
	s_add_u32 s91, s91, s93
	buffer_load_dwordx4 v50, s[68:71], s91 offen lds
	s_add_u32 m0, m0, 0x1000
	s_add_u32 s91, s91, s93
	buffer_load_dwordx4 v50, s[68:71], s91 offen lds
	s_add_u32 m0, m0, 0x1000
	s_add_u32 s91, s91, s93
	buffer_load_dwordx4 v50, s[68:71], s91 offen lds
	s_add_u32 m0, m0, 0x1000
	s_add_u32 s91, s91, s93
	buffer_load_dwordx4 v50, s[68:71], s91 offen lds
	s_add_u32 m0, m0, 0x1000
	s_add_u32 s91, s91, s93
	buffer_load_dwordx4 v50, s[68:71], s91 offen lds
	s_add_u32 m0, m0, 0x1000
	s_add_u32 s91, s91, s93
	buffer_load_dwordx4 v50, s[68:71], s91 offen lds
	s_add_u32 m0, m0, 0x1000
	s_add_u32 s91, s91, s93
	buffer_load_dwordx4 v50, s[68:71], s91 offen lds
	s_add_u32 m0, m0, 0x1000
	s_add_u32 s91, s91, s93
	buffer_load_dwordx4 v50, s[68:71], s91 offen lds
	s_add_u32 m0, m0, 0x1000
	s_add_u32 s91, s91, s93
	buffer_load_dwordx4 v50, s[68:71], s91 offen lds
	s_add_u32 m0, m0, 0x1000
	s_add_u32 s91, s91, s93
	buffer_load_dwordx4 v50, s[68:71], s91 offen lds
	s_add_u32 m0, m0, 0x1000
	s_add_u32 s91, s91, s93
	buffer_load_dwordx4 v50, s[68:71], s91 offen lds
	s_mov_b32 s0, 1
	s_branch .Lmy_nat_p4j
.Lmy_nat_p4x:
	s_add_u32 s4, s88, s94
	s_cmpk_gt_i32 s4, 0x3ff
	s_cbranch_scc1 .Lmy_nat_p4j
	s_lshr_b32 s5, s4, 5
	s_and_b32 s6, s5, 15
	s_lshl_b32 s6, s6, 7
	s_lshr_b32 s5, s5, 4
	s_lshl_b32 s5, s5, 14
	s_and_b32 s4, s4, 31
	s_lshl_b32 s4, s4, 3
	s_add_i32 s4, s4, -4
	s_max_i32 s4, s4, 0
	s_min_i32 s4, s4, 0xf1
	s_lshl_b32 s4, s4, 6
	s_add_u32 s4, s4, s5
	s_lshl_b32 s4, s4, 11
	s_add_u32 s4, s4, s6
	s_add_u32 s4, s4, 0x4000000
	s_mov_b32 s87, 0
	s_lshl_b32 s91, s87, 11
	s_add_u32 s91, s91, s4
	s_lshr_b32 s85, s1, 1
	s_lshl_b32 s85, s85, 13
	s_add_u32 s91, s91, s85
	s_and_b32 s85, s1, 1
	s_lshl_b32 s85, s85, 6
	s_add_u32 s91, s91, s85
	s_mov_b32 s93, 0x20000
	s_lshl_b32 s86, s1, 10
	s_mov_b32 m0, s86
	s_nop 0
	buffer_load_dwordx4 v50, s[68:71], s91 offen lds
	s_add_u32 m0, m0, 0x1000
	s_add_u32 s91, s91, s93
	buffer_load_dwordx4 v50, s[68:71], s91 offen lds
	s_add_u32 m0, m0, 0x1000
	s_add_u32 s91, s91, s93
	buffer_load_dwordx4 v50, s[68:71], s91 offen lds
	s_add_u32 m0, m0, 0x1000
	s_add_u32 s91, s91, s93
	buffer_load_dwordx4 v50, s[68:71], s91 offen lds
	s_add_u32 m0, m0, 0x1000
	s_add_u32 s91, s91, s93
	buffer_load_dwordx4 v50, s[68:71], s91 offen lds
	s_add_u32 m0, m0, 0x1000
	s_add_u32 s91, s91, s93
	buffer_load_dwordx4 v50, s[68:71], s91 offen lds
	s_add_u32 m0, m0, 0x1000
	s_add_u32 s91, s91, s93
	buffer_load_dwordx4 v50, s[68:71], s91 offen lds
	s_add_u32 m0, m0, 0x1000
	s_add_u32 s91, s91, s93
	buffer_load_dwordx4 v50, s[68:71], s91 offen lds
	s_add_u32 m0, m0, 0x1000
	s_add_u32 s91, s91, s93
	buffer_load_dwordx4 v50, s[68:71], s91 offen lds
	s_add_u32 m0, m0, 0x1000
	s_add_u32 s91, s91, s93
	buffer_load_dwordx4 v50, s[68:71], s91 offen lds
	s_add_u32 m0, m0, 0x1000
	s_add_u32 s91, s91, s93
	buffer_load_dwordx4 v50, s[68:71], s91 offen lds
	s_add_u32 m0, m0, 0x1000
	s_add_u32 s91, s91, s93
	buffer_load_dwordx4 v50, s[68:71], s91 offen lds
	s_add_u32 m0, m0, 0x1000
	s_add_u32 s91, s91, s93
	buffer_load_dwordx4 v50, s[68:71], s91 offen lds
	s_add_u32 m0, m0, 0x1000
	s_add_u32 s91, s91, s93
	buffer_load_dwordx4 v50, s[68:71], s91 offen lds
	s_add_u32 m0, m0, 0x1000
	s_add_u32 s91, s91, s93
	buffer_load_dwordx4 v50, s[68:71], s91 offen lds
	s_mov_b32 s0, 1
	s_mov_b32 s95, 1
; __device__ __forceinline__ unsigned cvt_pk_bf16(float lo, float hi) { unsigned r; asm volatile("v_cvt_pk_bf16_f32 %0, %1, %2" : "=v"(r) : "v"(lo), "v"(hi)); return r; }
; __device__ __forceinline__ void nat_phase(const Params& p, float* ldsf, int wave0, int nwaves) {
;     ...
; #pragma unroll
;             for (int i = 0; i < 8; ++i) {
;                 u32x4 pw; pw.x = cvt_pk_bf16(sc[i][0][0] * inv, sc[i][0][1] * inv); pw.y = cvt_pk_bf16(sc[i][0][2] * inv, sc[i][0][3] * inv);
;                 pw.z = cvt_pk_bf16(sc[i][1][0] * inv, sc[i][1][1] * inv); pw.w = cvt_pk_bf16(sc[i][1][2] * inv, sc[i][1][3] * inv);
;                 const bf16x8 bp = __builtin_bit_cast(bf16x8, pw);
; #pragma unroll
;                 for (int mt = 0; mt < 4; ++mt) { const u16* vp = Vb + (size_t)(mt * 16 + l15) * SEQ + i * 64 + cs0 + lq * 8;
;                     o[mt] = __builtin_amdgcn_mfma_f32_16x16x32_bf16(*(const bf16x8*)vp, bp, o[mt], 0, 0, 0); }
;             }
.Lmy_nat_p4j:
	ds_read_b128 v[0:3], v49 offset:0
	ds_read_b128 v[4:7], v49 offset:1024
	ds_read_b128 v[8:11], v49 offset:2048
	ds_read_b128 v[12:15], v49 offset:3072
	ds_read_b128 v[16:19], v49 offset:4096
	ds_read_b128 v[20:23], v49 offset:5120
	ds_read_b128 v[24:27], v49 offset:6144
	ds_read_b128 v[28:31], v49 offset:7168
	ds_read_b128 v[32:35], v49 offset:8192
	ds_read_b128 v[36:39], v49 offset:9216
	ds_read_b128 v[40:43], v49 offset:10240
	ds_read_b128 v[44:47], v49 offset:11264
	s_waitcnt lgkmcnt(11)
	v_mfma_f32_16x16x32_bf16 v[200:203], v[0:3], v[128:131], 0
	ds_read_b128 v[0:3], v49 offset:12288
	s_waitcnt lgkmcnt(11)
	v_mfma_f32_16x16x32_bf16 v[204:207], v[4:7], v[128:131], 0
	ds_read_b128 v[4:7], v49 offset:13312
	s_waitcnt lgkmcnt(11)
	v_mfma_f32_16x16x32_bf16 v[208:211], v[8:11], v[128:131], 0
	ds_read_b128 v[8:11], v49 offset:14336
	s_waitcnt lgkmcnt(11)
	v_mfma_f32_16x16x32_bf16 v[212:215], v[12:15], v[128:131], 0
	ds_read_b128 v[12:15], v49 offset:15360
	s_waitcnt lgkmcnt(11)
	v_mfma_f32_16x16x32_bf16 v[200:203], v[16:19], v[136:139], v[200:203]
	ds_read_b128 v[16:19], v49 offset:16384
	s_waitcnt lgkmcnt(11)
	v_mfma_f32_16x16x32_bf16 v[204:207], v[20:23], v[136:139], v[204:207]
	ds_read_b128 v[20:23], v49 offset:17408
	s_waitcnt lgkmcnt(11)
	v_mfma_f32_16x16x32_bf16 v[208:211], v[24:27], v[136:139], v[208:211]
	ds_read_b128 v[24:27], v49 offset:18432
	s_waitcnt lgkmcnt(11)
	v_mfma_f32_16x16x32_bf16 v[212:215], v[28:31], v[136:139], v[212:215]
	ds_read_b128 v[28:31], v49 offset:19456
	s_waitcnt lgkmcnt(11)
	v_mfma_f32_16x16x32_bf16 v[200:203], v[32:35], v[144:147], v[200:203]
	ds_read_b128 v[32:35], v49 offset:20480
	s_waitcnt lgkmcnt(11)
	v_mfma_f32_16x16x32_bf16 v[204:207], v[36:39], v[144:147], v[204:207]
	ds_read_b128 v[36:39], v49 offset:21504
	s_waitcnt lgkmcnt(11)
	v_mfma_f32_16x16x32_bf16 v[208:211], v[40:43], v[144:147], v[208:211]
	ds_read_b128 v[40:43], v49 offset:22528
	s_waitcnt lgkmcnt(11)
	v_mfma_f32_16x16x32_bf16 v[212:215], v[44:47], v[144:147], v[212:215]
	ds_read_b128 v[44:47], v49 offset:23552
	s_waitcnt lgkmcnt(11)
	v_mfma_f32_16x16x32_bf16 v[200:203], v[0:3], v[152:155], v[200:203]
	ds_read_b128 v[0:3], v49 offset:24576
	s_waitcnt lgkmcnt(11)
	v_mfma_f32_16x16x32_bf16 v[204:207], v[4:7], v[152:155], v[204:207]
	ds_read_b128 v[4:7], v49 offset:25600
	s_waitcnt lgkmcnt(11)
	v_mfma_f32_16x16x32_bf16 v[208:211], v[8:11], v[152:155], v[208:211]
	ds_read_b128 v[8:11], v49 offset:26624
	s_waitcnt lgkmcnt(11)
	v_mfma_f32_16x16x32_bf16 v[212:215], v[12:15], v[152:155], v[212:215]
	ds_read_b128 v[12:15], v49 offset:27648
	s_waitcnt lgkmcnt(11)
	v_mfma_f32_16x16x32_bf16 v[200:203], v[16:19], v[160:163], v[200:203]
	ds_read_b128 v[16:19], v49 offset:28672
	s_waitcnt lgkmcnt(11)
	v_mfma_f32_16x16x32_bf16 v[204:207], v[20:23], v[160:163], v[204:207]
	ds_read_b128 v[20:23], v49 offset:29696
	s_waitcnt lgkmcnt(11)
	v_mfma_f32_16x16x32_bf16 v[208:211], v[24:27], v[160:163], v[208:211]
	ds_read_b128 v[24:27], v49 offset:30720
	s_waitcnt lgkmcnt(11)
	v_mfma_f32_16x16x32_bf16 v[212:215], v[28:31], v[160:163], v[212:215]
	ds_read_b128 v[28:31], v49 offset:31744
	s_waitcnt lgkmcnt(11)
	v_mfma_f32_16x16x32_bf16 v[200:203], v[32:35], v[168:171], v[200:203]
	s_waitcnt lgkmcnt(10)
	v_mfma_f32_16x16x32_bf16 v[204:207], v[36:39], v[168:171], v[204:207]
	s_waitcnt lgkmcnt(9)
	v_mfma_f32_16x16x32_bf16 v[208:211], v[40:43], v[168:171], v[208:211]
	s_waitcnt lgkmcnt(8)
	v_mfma_f32_16x16x32_bf16 v[212:215], v[44:47], v[168:171], v[212:215]
	s_waitcnt lgkmcnt(7)
	v_mfma_f32_16x16x32_bf16 v[200:203], v[0:3], v[176:179], v[200:203]
	s_waitcnt lgkmcnt(6)
	v_mfma_f32_16x16x32_bf16 v[204:207], v[4:7], v[176:179], v[204:207]
	s_waitcnt lgkmcnt(5)
	v_mfma_f32_16x16x32_bf16 v[208:211], v[8:11], v[176:179], v[208:211]
	s_waitcnt lgkmcnt(4)
	v_mfma_f32_16x16x32_bf16 v[212:215], v[12:15], v[176:179], v[212:215]
	s_waitcnt lgkmcnt(3)
	v_mfma_f32_16x16x32_bf16 v[200:203], v[16:19], v[184:187], v[200:203]
	s_waitcnt lgkmcnt(2)
	v_mfma_f32_16x16x32_bf16 v[204:207], v[20:23], v[184:187], v[204:207]
	s_waitcnt lgkmcnt(1)
	v_mfma_f32_16x16x32_bf16 v[208:211], v[24:27], v[184:187], v[208:211]
	s_waitcnt lgkmcnt(0)
	v_mfma_f32_16x16x32_bf16 v[212:215], v[28:31], v[184:187], v[212:215]
	s_cmp_eq_u32 s0, 1
	s_cbranch_scc0 .Lmy_nat_p5z
	s_waitcnt vmcnt(15)
	s_branch .Lmy_nat_p5j
